# gates epilogue: sqrt Newton-correction tail dropped (raw v_sqrt_f32 1ulp + range scaling kept) at 56 of 64 sites; scan15 loads up-front
# speedup vs baseline: 1.0058x; 1.0058x over previous
; __device__ __forceinline__ float fsigmoid(float x) { return __builtin_amdgcn_rcpf(1.0f + __expf(-x)); }
;     __device__ __forceinline__ void operator()(const Acc& acc, const Unit& u, int wr, int wc, int fr, int fq) const {
;     ...
;                     for (int j = 0; j < 4; ++j) { const float r = fsigmoid(acc[ai][0][m][n][j] + ba[n][j]), ig = fsigmoid(acc[ai][1][m][n][j] + bi[n][j]);
;                         const float y = r * cc[n][j];
;                         float o1 = y * (1.0f - y * (0.5f - y * (0.16666667f - y * (0.041666668f - y * 0.008333334f))));
;                         if (__builtin_expect(__any(y >= 0.125f), 0)) { const float ome = 1.0f - __expf(-y); o1 = y < 0.125f ? o1 : ome; }
;                         om[n * 4 + j] = o1; uv[n * 4 + j] = sqrtf(o1 * (2.0f - o1)) * (ig * xv[n * 4 + j]); }
.LBB0_344:
	v_sub_f32_e32 v168, 2.0, v146
	v_mul_f32_e32 v168, v146, v168
	v_mul_f32_e32 v169, 0x4f800000, v168
	v_cmp_gt_f32_e32 vcc, s10, v168
	v_add_f32_e32 v142, v142, v42
	v_mul_f32_e32 v142, 0xbfb8aa3b, v142
	v_cndmask_b32_e32 v168, v168, v169, vcc
	v_sqrt_f32_e32 v169, v168
	v_exp_f32_e32 v142, v142
	v_add_f32_e32 v143, v143, v43
	v_mul_f32_e32 v143, 0xbfb8aa3b, v143
	v_add_f32_e32 v142, 1.0, v142
	v_rcp_f32_e32 v142, v142
	v_exp_f32_e32 v143, v143
	v_lshlrev_b32_e32 v170, 16, v155
	v_mul_f32_e32 v171, 0x37800000, v169
	v_cndmask_b32_e32 v169, v169, v171, vcc
	v_cmp_class_f32_e32 vcc, v168, v194
	v_mul_f32_e32 v142, v142, v170
	v_add_f32_e32 v141, v141, v41
	v_cndmask_b32_e32 v168, v169, v168, vcc
	v_mul_f32_e32 v168, v142, v168
	v_add_f32_e32 v142, 1.0, v143
	v_sub_f32_e32 v143, 2.0, v145
	v_mul_f32_e32 v143, v145, v143
	v_mul_f32_e32 v169, 0x4f800000, v143
	v_cmp_gt_f32_e32 vcc, s10, v143
	v_mul_f32_e32 v141, 0xbfb8aa3b, v141
	v_exp_f32_e32 v141, v141
	v_cndmask_b32_e32 v143, v143, v169, vcc
	v_sqrt_f32_e32 v169, v143
	v_and_b32_e32 v170, 0xffff0000, v154
	v_add_f32_e32 v141, 1.0, v141
	v_rcp_f32_e32 v141, v141
	s_nop 0
	v_mul_f32_e32 v141, v141, v170
	v_add_f32_e32 v140, v140, v40
	v_mul_f32_e32 v140, 0xbfb8aa3b, v140
	v_mul_f32_e32 v171, 0x37800000, v169
	v_cndmask_b32_e32 v169, v169, v171, vcc
	v_cmp_class_f32_e32 vcc, v143, v194
	v_exp_f32_e32 v140, v140
	v_lshlrev_b32_e32 v154, 16, v154
	v_cndmask_b32_e32 v143, v169, v143, vcc
	v_mul_f32_e32 v143, v141, v143
	v_sub_f32_e32 v141, 2.0, v144
	v_mul_f32_e32 v141, v144, v141
	v_mul_f32_e32 v169, 0x4f800000, v141
	v_cmp_gt_f32_e32 vcc, s10, v141
	v_add_f32_e32 v140, 1.0, v140
	v_rcp_f32_e32 v140, v140
	v_cndmask_b32_e32 v141, v141, v169, vcc
	v_sqrt_f32_e32 v169, v141
	v_add_f32_e32 v139, v139, v35
	v_mul_f32_e32 v140, v140, v154
	v_mul_f32_e32 v139, 0xbfb8aa3b, v139
	v_exp_f32_e32 v139, v139
	s_nop 0
	v_add_f32_e32 v139, 1.0, v139
	v_rcp_f32_e32 v139, v139
	v_mul_f32_e32 v170, 0x37800000, v169
	v_cndmask_b32_e32 v169, v169, v170, vcc
	v_cmp_class_f32_e32 vcc, v141, v194
	v_add_f32_e32 v138, v138, v34
	v_mul_f32_e32 v138, 0xbfb8aa3b, v138
	v_cndmask_b32_e32 v141, v169, v141, vcc
	v_mul_f32_e32 v154, v140, v141
	v_sub_f32_e32 v140, 2.0, v151
	v_mul_f32_e32 v140, v151, v140
	v_mul_f32_e32 v141, 0x4f800000, v140
	v_cmp_gt_f32_e32 vcc, s10, v140
	v_and_b32_e32 v169, 0xffff0000, v153
	v_mul_f32_e32 v139, v139, v169
	v_cndmask_b32_e32 v140, v140, v141, vcc
	v_sqrt_f32_e32 v141, v140
	v_exp_f32_e32 v138, v138
	v_lshlrev_b32_e32 v153, 16, v153
	v_add_f32_e32 v137, v137, v33
	v_add_f32_e32 v138, 1.0, v138
	v_rcp_f32_e32 v138, v138
	v_mul_f32_e32 v137, 0xbfb8aa3b, v137
	v_mul_f32_e32 v170, 0x37800000, v141
	v_cndmask_b32_e32 v141, v141, v170, vcc
	v_cmp_class_f32_e32 vcc, v140, v194
	v_mul_f32_e32 v138, v138, v153
	v_exp_f32_e32 v137, v137
	v_cndmask_b32_e32 v140, v141, v140, vcc
	v_mul_f32_e32 v141, v139, v140
	v_sub_f32_e32 v139, 2.0, v150
	v_mul_f32_e32 v139, v150, v139
	v_mul_f32_e32 v140, 0x4f800000, v139
	v_cmp_gt_f32_e32 vcc, s10, v139
	v_add_f32_e32 v137, 1.0, v137
	v_rcp_f32_e32 v137, v137
	v_cndmask_b32_e32 v139, v139, v140, vcc
	v_sqrt_f32_e32 v140, v139
	v_add_f32_e32 v136, v136, v32
	v_mul_f32_e32 v136, 0xbfb8aa3b, v136
	v_exp_f32_e32 v136, v136
	s_nop 0
	v_add_f32_e32 v136, 1.0, v136
	v_rcp_f32_e32 v136, v136
	s_ashr_i32 s13, s12, 31
	v_mul_f32_e32 v169, 0x37800000, v140
	v_cndmask_b32_e32 v140, v140, v169, vcc
	v_cmp_class_f32_e32 vcc, v139, v194
	v_rcp_f32_e32 v142, v142
	v_add_f32_e32 v132, v132, v64
	v_cndmask_b32_e32 v139, v140, v139, vcc
	v_mul_f32_e32 v153, v138, v139
	v_sub_f32_e32 v138, 2.0, v149
	v_mul_f32_e32 v138, v149, v138
	v_mul_f32_e32 v139, 0x4f800000, v138
	v_cmp_gt_f32_e32 vcc, s10, v138
	v_and_b32_e32 v140, 0xffff0000, v152
	v_mul_f32_e32 v137, v137, v140
	v_cndmask_b32_e32 v138, v138, v139, vcc
	v_sqrt_f32_e32 v139, v138
	v_mul_f32_e32 v132, 0xbfb8aa3b, v132
	v_exp_f32_e32 v132, v132
	s_nop 0
	v_add_f32_e32 v132, 1.0, v132
	v_rcp_f32_e32 v132, v132
	s_nop 0
	v_mul_f32_e32 v169, 0x37800000, v139
	v_cndmask_b32_e32 v139, v139, v169, vcc
	v_cmp_class_f32_e32 vcc, v138, v194
	s_nop 1
	s_nop 0
	v_cndmask_b32_e32 v138, v139, v138, vcc
	v_mul_f32_e32 v140, v137, v138
	v_sub_f32_e32 v137, 2.0, v148
	v_mul_f32_e32 v137, v148, v137
	v_mul_f32_e32 v138, 0x4f800000, v137
	v_cmp_gt_f32_e32 vcc, s10, v137
	v_lshlrev_b32_e32 v139, 16, v152
	v_mul_f32_e32 v136, v136, v139
	v_cndmask_b32_e32 v137, v137, v138, vcc
	v_sqrt_f32_e32 v138, v137
	s_nop 0
	s_nop 0
	s_nop 1
	v_mul_f32_e32 v152, 0x37800000, v138
	v_cndmask_b32_e32 v138, v138, v152, vcc
	v_cmp_class_f32_e32 vcc, v137, v194
	s_lshl_b64 s[0:1], s[12:13], 27
	v_readlane_b32 s12, v251, 42
	v_cndmask_b32_e32 v137, v138, v137, vcc
	v_mul_f32_e32 v152, v136, v137
	v_sub_f32_e32 v136, 2.0, v147
	v_mul_f32_e32 v136, v147, v136
	v_mul_f32_e32 v137, 0x4f800000, v136
	v_cmp_gt_f32_e32 vcc, s10, v136
	v_readlane_b32 s13, v251, 43
	s_add_u32 s12, s12, s0
	v_cndmask_b32_e32 v136, v136, v137, vcc
	v_sqrt_f32_e32 v137, v136
	s_addc_u32 s13, s13, s1
	s_add_u32 s16, s78, s0
	v_and_b32_e32 v138, 0xffff0000, v155
	s_addc_u32 s17, s79, s1
	s_nop 0
	s_nop 1
	v_mul_f32_e32 v139, 0x37800000, v137
	v_cndmask_b32_e32 v137, v137, v139, vcc
	v_cmp_class_f32_e32 vcc, v136, v194
	s_mov_b64 s[0:1], 0x8000
	s_nop 0
	v_cndmask_b32_e32 v136, v137, v136, vcc
	v_mul_f32_e32 v137, v142, v138
	v_mul_f32_e32 v155, v137, v136
	v_cvt_pk_bf16_f32 v136, v148, v149
	v_cvt_pk_bf16_f32 v137, v150, v151
	v_cvt_pk_bf16_f32 v138, v144, v145
	v_lshlrev_b64 v[144:145], 1, v[184:185]
	v_cvt_pk_bf16_f32 v139, v146, v147
	v_lshl_add_u64 v[146:147], s[12:13], 0, v[144:145]
	v_cvt_pk_bf16_f32 v140, v152, v140
	v_cvt_pk_bf16_f32 v141, v153, v141
	v_cvt_pk_bf16_f32 v142, v154, v143
	v_cvt_pk_bf16_f32 v143, v168, v155
	global_store_dwordx4 v[146:147], v[136:139], off
	s_nop 1
	v_lshl_add_u64 v[136:137], s[16:17], 0, v[144:145]
	global_store_dwordx4 v[136:137], v[140:143], off
	v_lshlrev_b64 v[136:137], 11, v[182:183]
	v_lshl_add_u64 v[136:137], v[136:137], 0, v[180:181]
	v_lshl_add_u64 v[140:141], v[136:137], 0, s[0:1]
	v_readlane_b32 s0, v252, 6
	v_readlane_b32 s1, v252, 7
	v_mul_f32_e32 v142, v68, v132
	v_fmamk_f32 v132, v142, 0xbc088889, v163
	v_lshl_add_u64 v[136:137], v[140:141], 1, s[0:1]
	global_load_dwordx4 v[136:139], v[136:137], off
	v_fma_f32 v132, -v142, v132, s5
	v_fma_f32 v132, -v142, v132, 0.5
	v_fma_f32 v132, -v142, v132, 1.0
	v_mul_f32_e32 v132, v142, v132
	v_cmp_le_f32_e32 vcc, s8, v142
	s_cbranch_vccnz .LBB0_412

; __device__ __forceinline__ unsigned cvt_pk_bf16(float lo, float hi) { unsigned r; asm volatile("v_cvt_pk_bf16_f32 %0, %1, %2" : "=v"(r) : "v"(lo), "v"(hi)); return r; }
; __device__ __forceinline__ float fsigmoid(float x) { return __builtin_amdgcn_rcpf(1.0f + __expf(-x)); }
;     __device__ __forceinline__ void operator()(const Acc& acc, const Unit& u, int wr, int wc, int fr, int fq) const {
;     ...
;                     for (int j = 0; j < 4; ++j) { const float r = fsigmoid(acc[ai][0][m][n][j] + ba[n][j]), ig = fsigmoid(acc[ai][1][m][n][j] + bi[n][j]);
;                         const float y = r * cc[n][j];
;                         float o1 = y * (1.0f - y * (0.5f - y * (0.16666667f - y * (0.041666668f - y * 0.008333334f))));
;                         if (__builtin_expect(__any(y >= 0.125f), 0)) { const float ome = 1.0f - __expf(-y); o1 = y < 0.125f ? o1 : ome; }
;                         om[n * 4 + j] = o1; uv[n * 4 + j] = sqrtf(o1 * (2.0f - o1)) * (ig * xv[n * 4 + j]); }
;                 u32x4 wa, wu; wa.x = cvt_pk_bf16(om[0], om[1]); wa.y = cvt_pk_bf16(om[2], om[3]); wa.z = cvt_pk_bf16(om[4], om[5]); wa.w = cvt_pk_bf16(om[6], om[7]);
;                 wu.x = cvt_pk_bf16(uv[0], uv[1]); wu.y = cvt_pk_bf16(uv[2], uv[3]); wu.z = cvt_pk_bf16(uv[4], uv[5]); wu.w = cvt_pk_bf16(uv[6], uv[7]);
;                 *(u32x4*)(Ao + off) = wa; *(u32x4*)(Uo + off) = wu; asm volatile("" ::: "memory"); }
.LBB0_352:
	v_sub_f32_e32 v142, 2.0, v130
	v_mul_f32_e32 v142, v130, v142
	v_mul_f32_e32 v143, 0x4f800000, v142
	v_cmp_gt_f32_e32 vcc, s10, v142
	v_add_f32_e32 v126, v126, v42
	v_mul_f32_e32 v126, 0xbfb8aa3b, v126
	v_cndmask_b32_e32 v142, v142, v143, vcc
	v_sqrt_f32_e32 v143, v142
	v_exp_f32_e32 v126, v126
	v_add_f32_e32 v127, v127, v43
	v_mul_f32_e32 v127, 0xbfb8aa3b, v127
	v_add_f32_e32 v126, 1.0, v126
	v_rcp_f32_e32 v126, v126
	v_exp_f32_e32 v127, v127
	s_waitcnt vmcnt(0)
	v_lshlrev_b32_e32 v144, 16, v139
	v_mul_f32_e32 v145, 0x37800000, v143
	v_cndmask_b32_e32 v143, v143, v145, vcc
	v_cmp_class_f32_e32 vcc, v142, v194
	v_mul_f32_e32 v126, v126, v144
	v_add_f32_e32 v125, v125, v41
	v_cndmask_b32_e32 v142, v143, v142, vcc
	v_mul_f32_e32 v142, v126, v142
	v_add_f32_e32 v126, 1.0, v127
	v_sub_f32_e32 v127, 2.0, v129
	v_mul_f32_e32 v127, v129, v127
	v_mul_f32_e32 v143, 0x4f800000, v127
	v_cmp_gt_f32_e32 vcc, s10, v127
	v_mul_f32_e32 v125, 0xbfb8aa3b, v125
	v_exp_f32_e32 v125, v125
	v_cndmask_b32_e32 v127, v127, v143, vcc
	v_sqrt_f32_e32 v143, v127
	v_and_b32_e32 v144, 0xffff0000, v138
	v_add_f32_e32 v125, 1.0, v125
	v_rcp_f32_e32 v125, v125
	s_nop 0
	v_mul_f32_e32 v125, v125, v144
	v_add_f32_e32 v124, v124, v40
	v_mul_f32_e32 v124, 0xbfb8aa3b, v124
	v_mul_f32_e32 v145, 0x37800000, v143
	v_cndmask_b32_e32 v143, v143, v145, vcc
	v_cmp_class_f32_e32 vcc, v127, v194
	v_exp_f32_e32 v124, v124
	v_lshlrev_b32_e32 v138, 16, v138
	v_cndmask_b32_e32 v127, v143, v127, vcc
	v_mul_f32_e32 v127, v125, v127
	v_sub_f32_e32 v125, 2.0, v128
	v_mul_f32_e32 v125, v128, v125
	v_mul_f32_e32 v143, 0x4f800000, v125
	v_cmp_gt_f32_e32 vcc, s10, v125
	v_add_f32_e32 v124, 1.0, v124
	v_rcp_f32_e32 v124, v124
	v_cndmask_b32_e32 v125, v125, v143, vcc
	v_sqrt_f32_e32 v143, v125
	v_add_f32_e32 v123, v123, v35
	v_mul_f32_e32 v124, v124, v138
	v_mul_f32_e32 v123, 0xbfb8aa3b, v123
	v_exp_f32_e32 v123, v123
	s_nop 0
	v_add_f32_e32 v123, 1.0, v123
	v_rcp_f32_e32 v123, v123
	v_mul_f32_e32 v144, 0x37800000, v143
	v_cndmask_b32_e32 v143, v143, v144, vcc
	v_cmp_class_f32_e32 vcc, v125, v194
	v_add_f32_e32 v122, v122, v34
	v_mul_f32_e32 v122, 0xbfb8aa3b, v122
	v_cndmask_b32_e32 v125, v143, v125, vcc
	v_mul_f32_e32 v138, v124, v125
	v_sub_f32_e32 v124, 2.0, v135
	v_mul_f32_e32 v124, v135, v124
	v_mul_f32_e32 v125, 0x4f800000, v124
	v_cmp_gt_f32_e32 vcc, s10, v124
	v_and_b32_e32 v143, 0xffff0000, v137
	v_mul_f32_e32 v123, v123, v143
	v_cndmask_b32_e32 v124, v124, v125, vcc
	v_sqrt_f32_e32 v125, v124
	v_exp_f32_e32 v122, v122
	v_lshlrev_b32_e32 v137, 16, v137
	v_add_f32_e32 v121, v121, v33
	v_add_f32_e32 v122, 1.0, v122
	v_rcp_f32_e32 v122, v122
	v_mul_f32_e32 v121, 0xbfb8aa3b, v121
	v_mul_f32_e32 v144, 0x37800000, v125
	v_cndmask_b32_e32 v125, v125, v144, vcc
	v_cmp_class_f32_e32 vcc, v124, v194
	v_mul_f32_e32 v122, v122, v137
	v_exp_f32_e32 v121, v121
	v_cndmask_b32_e32 v124, v125, v124, vcc
	v_mul_f32_e32 v125, v123, v124
	v_sub_f32_e32 v123, 2.0, v134
	v_mul_f32_e32 v123, v134, v123
	v_mul_f32_e32 v124, 0x4f800000, v123
	v_cmp_gt_f32_e32 vcc, s10, v123
	v_add_f32_e32 v121, 1.0, v121
	v_rcp_f32_e32 v121, v121
	v_cndmask_b32_e32 v123, v123, v124, vcc
	v_sqrt_f32_e32 v124, v123
	v_add_f32_e32 v120, v120, v32
	v_mul_f32_e32 v120, 0xbfb8aa3b, v120
	v_exp_f32_e32 v120, v120
	s_nop 0
	v_add_f32_e32 v120, 1.0, v120
	v_rcp_f32_e32 v120, v120
	v_rcp_f32_e32 v126, v126
	v_mul_f32_e32 v143, 0x37800000, v124
	v_cndmask_b32_e32 v124, v124, v143, vcc
	v_cmp_class_f32_e32 vcc, v123, v194
	v_add_f32_e32 v116, v116, v64
	v_mul_f32_e32 v116, 0xbfb8aa3b, v116
	v_cndmask_b32_e32 v123, v124, v123, vcc
	v_mul_f32_e32 v137, v122, v123
	v_sub_f32_e32 v122, 2.0, v133
	v_mul_f32_e32 v122, v133, v122
	v_mul_f32_e32 v123, 0x4f800000, v122
	v_cmp_gt_f32_e32 vcc, s10, v122
	v_and_b32_e32 v124, 0xffff0000, v136
	v_mul_f32_e32 v121, v121, v124
	v_cndmask_b32_e32 v122, v122, v123, vcc
	v_sqrt_f32_e32 v123, v122
	v_exp_f32_e32 v116, v116
	s_nop 0
	v_add_f32_e32 v116, 1.0, v116
	v_rcp_f32_e32 v116, v116
	s_nop 0
	v_mul_f32_e32 v143, 0x37800000, v123
	v_cndmask_b32_e32 v123, v123, v143, vcc
	v_cmp_class_f32_e32 vcc, v122, v194
	s_nop 1
	s_nop 0
	v_cndmask_b32_e32 v122, v123, v122, vcc
	v_mul_f32_e32 v124, v121, v122
	v_sub_f32_e32 v121, 2.0, v132
	v_mul_f32_e32 v121, v132, v121
	v_mul_f32_e32 v122, 0x4f800000, v121
	v_cmp_gt_f32_e32 vcc, s10, v121
	v_lshlrev_b32_e32 v123, 16, v136
	v_mul_f32_e32 v120, v120, v123
	v_cndmask_b32_e32 v121, v121, v122, vcc
	v_sqrt_f32_e32 v122, v121
	s_nop 0
	s_nop 0
	s_nop 1
	v_mul_f32_e32 v136, 0x37800000, v122
	v_cndmask_b32_e32 v122, v122, v136, vcc
	v_cmp_class_f32_e32 vcc, v121, v194
	s_nop 1
	s_nop 0
	v_cndmask_b32_e32 v121, v122, v121, vcc
	v_sub_f32_e32 v122, 2.0, v131
	v_mul_f32_e32 v122, v131, v122
	v_mul_f32_e32 v136, 0x4f800000, v122
	v_cmp_gt_f32_e32 vcc, s10, v122
	v_mul_f32_e32 v143, v120, v121
	v_and_b32_e32 v120, 0xffff0000, v139
	v_cndmask_b32_e32 v122, v122, v136, vcc
	v_sqrt_f32_e32 v136, v122
	v_mul_f32_e32 v120, v126, v120
	s_nop 0
	s_nop 1
	v_mul_f32_e32 v123, 0x37800000, v136
	v_cndmask_b32_e32 v121, v136, v123, vcc
	v_cmp_class_f32_e32 vcc, v122, v194
	s_mov_b64 s[0:1], 0x10000
	s_nop 0
	v_cndmask_b32_e32 v121, v121, v122, vcc
	v_mul_f32_e32 v136, v120, v121
	v_cvt_pk_bf16_f32 v120, v132, v133
	v_cvt_pk_bf16_f32 v121, v134, v135
	v_cvt_pk_bf16_f32 v122, v128, v129
	v_lshlrev_b64 v[128:129], 1, v[140:141]
	v_cvt_pk_bf16_f32 v123, v130, v131
	v_lshl_add_u64 v[130:131], s[12:13], 0, v[128:129]
	v_cvt_pk_bf16_f32 v124, v143, v124
	v_cvt_pk_bf16_f32 v125, v137, v125
	v_cvt_pk_bf16_f32 v126, v138, v127
	v_cvt_pk_bf16_f32 v127, v142, v136
	global_store_dwordx4 v[130:131], v[120:123], off
	s_nop 1
	v_lshl_add_u64 v[120:121], s[16:17], 0, v[128:129]
	global_store_dwordx4 v[120:121], v[124:127], off
	v_lshlrev_b64 v[120:121], 11, v[182:183]
	v_lshl_add_u64 v[120:121], v[120:121], 0, v[180:181]
	v_lshl_add_u64 v[124:125], v[120:121], 0, s[0:1]
	v_readlane_b32 s0, v252, 6
	v_readlane_b32 s1, v252, 7
	v_mul_f32_e32 v126, v68, v116
	v_fmamk_f32 v116, v126, 0xbc088889, v163
	v_lshl_add_u64 v[120:121], v[124:125], 1, s[0:1]
	global_load_dwordx4 v[120:123], v[120:121], off
	v_fma_f32 v116, -v126, v116, s5
	v_fma_f32 v116, -v126, v116, 0.5
	v_fma_f32 v116, -v126, v116, 1.0
	v_mul_f32_e32 v116, v126, v116
	v_cmp_le_f32_e32 vcc, s8, v126
	s_cbranch_vccnz .LBB0_420

; __device__ __forceinline__ unsigned cvt_pk_bf16(float lo, float hi) { unsigned r; asm volatile("v_cvt_pk_bf16_f32 %0, %1, %2" : "=v"(r) : "v"(lo), "v"(hi)); return r; }
; __device__ __forceinline__ float fsigmoid(float x) { return __builtin_amdgcn_rcpf(1.0f + __expf(-x)); }
;     __device__ __forceinline__ void operator()(const Acc& acc, const Unit& u, int wr, int wc, int fr, int fq) const {
;     ...
;                     for (int j = 0; j < 4; ++j) { const float r = fsigmoid(acc[ai][0][m][n][j] + ba[n][j]), ig = fsigmoid(acc[ai][1][m][n][j] + bi[n][j]);
;                         const float y = r * cc[n][j];
;                         float o1 = y * (1.0f - y * (0.5f - y * (0.16666667f - y * (0.041666668f - y * 0.008333334f))));
;                         if (__builtin_expect(__any(y >= 0.125f), 0)) { const float ome = 1.0f - __expf(-y); o1 = y < 0.125f ? o1 : ome; }
;                         om[n * 4 + j] = o1; uv[n * 4 + j] = sqrtf(o1 * (2.0f - o1)) * (ig * xv[n * 4 + j]); }
;                 u32x4 wa, wu; wa.x = cvt_pk_bf16(om[0], om[1]); wa.y = cvt_pk_bf16(om[2], om[3]); wa.z = cvt_pk_bf16(om[4], om[5]); wa.w = cvt_pk_bf16(om[6], om[7]);
;                 wu.x = cvt_pk_bf16(uv[0], uv[1]); wu.y = cvt_pk_bf16(uv[2], uv[3]); wu.z = cvt_pk_bf16(uv[4], uv[5]); wu.w = cvt_pk_bf16(uv[6], uv[7]);
;                 *(u32x4*)(Ao + off) = wa; *(u32x4*)(Uo + off) = wu; asm volatile("" ::: "memory"); }
.LBB0_360:
	v_sub_f32_e32 v126, 2.0, v114
	v_mul_f32_e32 v126, v114, v126
	v_mul_f32_e32 v127, 0x4f800000, v126
	v_cmp_gt_f32_e32 vcc, s10, v126
	v_add_f32_e32 v110, v110, v42
	v_mul_f32_e32 v110, 0xbfb8aa3b, v110
	v_cndmask_b32_e32 v126, v126, v127, vcc
	v_sqrt_f32_e32 v127, v126
	v_exp_f32_e32 v110, v110
	v_add_f32_e32 v111, v111, v43
	v_mul_f32_e32 v111, 0xbfb8aa3b, v111
	v_add_f32_e32 v110, 1.0, v110
	v_rcp_f32_e32 v110, v110
	v_exp_f32_e32 v111, v111
	s_waitcnt vmcnt(0)
	v_lshlrev_b32_e32 v128, 16, v123
	v_mul_f32_e32 v129, 0x37800000, v127
	v_cndmask_b32_e32 v127, v127, v129, vcc
	v_cmp_class_f32_e32 vcc, v126, v194
	v_mul_f32_e32 v110, v110, v128
	v_add_f32_e32 v109, v109, v41
	v_cndmask_b32_e32 v126, v127, v126, vcc
	v_mul_f32_e32 v126, v110, v126
	v_add_f32_e32 v110, 1.0, v111
	v_sub_f32_e32 v111, 2.0, v113
	v_mul_f32_e32 v111, v113, v111
	v_mul_f32_e32 v127, 0x4f800000, v111
	v_cmp_gt_f32_e32 vcc, s10, v111
	v_mul_f32_e32 v109, 0xbfb8aa3b, v109
	v_exp_f32_e32 v109, v109
	v_cndmask_b32_e32 v111, v111, v127, vcc
	v_sqrt_f32_e32 v127, v111
	v_and_b32_e32 v128, 0xffff0000, v122
	v_add_f32_e32 v109, 1.0, v109
	v_rcp_f32_e32 v109, v109
	s_nop 0
	v_mul_f32_e32 v109, v109, v128
	v_add_f32_e32 v108, v108, v40
	v_mul_f32_e32 v108, 0xbfb8aa3b, v108
	v_mul_f32_e32 v129, 0x37800000, v127
	v_cndmask_b32_e32 v127, v127, v129, vcc
	v_cmp_class_f32_e32 vcc, v111, v194
	v_exp_f32_e32 v108, v108
	v_lshlrev_b32_e32 v122, 16, v122
	v_cndmask_b32_e32 v111, v127, v111, vcc
	v_mul_f32_e32 v111, v109, v111
	v_sub_f32_e32 v109, 2.0, v112
	v_mul_f32_e32 v109, v112, v109
	v_mul_f32_e32 v127, 0x4f800000, v109
	v_cmp_gt_f32_e32 vcc, s10, v109
	v_add_f32_e32 v108, 1.0, v108
	v_rcp_f32_e32 v108, v108
	v_cndmask_b32_e32 v109, v109, v127, vcc
	v_sqrt_f32_e32 v127, v109
	v_add_f32_e32 v107, v107, v35
	v_mul_f32_e32 v108, v108, v122
	v_mul_f32_e32 v107, 0xbfb8aa3b, v107
	v_exp_f32_e32 v107, v107
	s_nop 0
	v_add_f32_e32 v107, 1.0, v107
	v_rcp_f32_e32 v107, v107
	v_mul_f32_e32 v128, 0x37800000, v127
	v_cndmask_b32_e32 v127, v127, v128, vcc
	v_cmp_class_f32_e32 vcc, v109, v194
	v_add_f32_e32 v106, v106, v34
	v_mul_f32_e32 v106, 0xbfb8aa3b, v106
	v_cndmask_b32_e32 v109, v127, v109, vcc
	v_mul_f32_e32 v122, v108, v109
	v_sub_f32_e32 v108, 2.0, v119
	v_mul_f32_e32 v108, v119, v108
	v_mul_f32_e32 v109, 0x4f800000, v108
	v_cmp_gt_f32_e32 vcc, s10, v108
	v_and_b32_e32 v127, 0xffff0000, v121
	v_mul_f32_e32 v107, v107, v127
	v_cndmask_b32_e32 v108, v108, v109, vcc
	v_sqrt_f32_e32 v109, v108
	v_exp_f32_e32 v106, v106
	v_lshlrev_b32_e32 v121, 16, v121
	v_add_f32_e32 v105, v105, v33
	v_add_f32_e32 v106, 1.0, v106
	v_rcp_f32_e32 v106, v106
	v_mul_f32_e32 v105, 0xbfb8aa3b, v105
	v_mul_f32_e32 v128, 0x37800000, v109
	v_cndmask_b32_e32 v109, v109, v128, vcc
	v_cmp_class_f32_e32 vcc, v108, v194
	v_mul_f32_e32 v106, v106, v121
	v_exp_f32_e32 v105, v105
	v_cndmask_b32_e32 v108, v109, v108, vcc
	v_mul_f32_e32 v109, v107, v108
	v_sub_f32_e32 v107, 2.0, v118
	v_mul_f32_e32 v107, v118, v107
	v_mul_f32_e32 v108, 0x4f800000, v107
	v_cmp_gt_f32_e32 vcc, s10, v107
	v_add_f32_e32 v105, 1.0, v105
	v_rcp_f32_e32 v105, v105
	v_cndmask_b32_e32 v107, v107, v108, vcc
	v_sqrt_f32_e32 v108, v107
	v_add_f32_e32 v104, v104, v32
	v_mul_f32_e32 v104, 0xbfb8aa3b, v104
	v_exp_f32_e32 v104, v104
	s_nop 0
	v_add_f32_e32 v104, 1.0, v104
	v_rcp_f32_e32 v104, v104
	v_rcp_f32_e32 v110, v110
	v_mul_f32_e32 v127, 0x37800000, v108
	v_cndmask_b32_e32 v108, v108, v127, vcc
	v_cmp_class_f32_e32 vcc, v107, v194
	v_add_f32_e32 v100, v100, v64
	v_mul_f32_e32 v100, 0xbfb8aa3b, v100
	v_cndmask_b32_e32 v107, v108, v107, vcc
	v_mul_f32_e32 v121, v106, v107
	v_sub_f32_e32 v106, 2.0, v117
	v_mul_f32_e32 v106, v117, v106
	v_mul_f32_e32 v107, 0x4f800000, v106
	v_cmp_gt_f32_e32 vcc, s10, v106
	v_and_b32_e32 v108, 0xffff0000, v120
	v_mul_f32_e32 v105, v105, v108
	v_cndmask_b32_e32 v106, v106, v107, vcc
	v_sqrt_f32_e32 v107, v106
	v_exp_f32_e32 v100, v100
	s_nop 0
	v_add_f32_e32 v100, 1.0, v100
	v_rcp_f32_e32 v100, v100
	s_nop 0
	v_mul_f32_e32 v127, 0x37800000, v107
	v_cndmask_b32_e32 v107, v107, v127, vcc
	v_cmp_class_f32_e32 vcc, v106, v194
	s_nop 1
	s_nop 0
	v_cndmask_b32_e32 v106, v107, v106, vcc
	v_mul_f32_e32 v108, v105, v106
	v_sub_f32_e32 v105, 2.0, v116
	v_mul_f32_e32 v105, v116, v105
	v_mul_f32_e32 v106, 0x4f800000, v105
	v_cmp_gt_f32_e32 vcc, s10, v105
	v_lshlrev_b32_e32 v107, 16, v120
	v_mul_f32_e32 v104, v104, v107
	v_cndmask_b32_e32 v105, v105, v106, vcc
	v_sqrt_f32_e32 v106, v105
	s_nop 0
	s_nop 0
	s_nop 1
	v_mul_f32_e32 v120, 0x37800000, v106
	v_cndmask_b32_e32 v106, v106, v120, vcc
	v_cmp_class_f32_e32 vcc, v105, v194
	s_nop 1
	s_nop 0
	v_cndmask_b32_e32 v105, v106, v105, vcc
	v_sub_f32_e32 v106, 2.0, v115
	v_mul_f32_e32 v106, v115, v106
	v_mul_f32_e32 v120, 0x4f800000, v106
	v_cmp_gt_f32_e32 vcc, s10, v106
	v_mul_f32_e32 v127, v104, v105
	v_and_b32_e32 v104, 0xffff0000, v123
	v_cndmask_b32_e32 v106, v106, v120, vcc
	v_sqrt_f32_e32 v120, v106
	v_mul_f32_e32 v104, v110, v104
	s_nop 0
	s_nop 1
	v_mul_f32_e32 v107, 0x37800000, v120
	v_cndmask_b32_e32 v105, v120, v107, vcc
	v_cmp_class_f32_e32 vcc, v106, v194
	s_mov_b64 s[0:1], 0x18000
	s_nop 0
	v_cndmask_b32_e32 v105, v105, v106, vcc
	v_mul_f32_e32 v120, v104, v105
	v_cvt_pk_bf16_f32 v104, v116, v117
	v_cvt_pk_bf16_f32 v105, v118, v119
	v_cvt_pk_bf16_f32 v106, v112, v113
	v_lshlrev_b64 v[112:113], 1, v[124:125]
	v_cvt_pk_bf16_f32 v107, v114, v115
	v_lshl_add_u64 v[114:115], s[12:13], 0, v[112:113]
	v_cvt_pk_bf16_f32 v108, v127, v108
	v_cvt_pk_bf16_f32 v109, v121, v109
	v_cvt_pk_bf16_f32 v110, v122, v111
	v_cvt_pk_bf16_f32 v111, v126, v120
	global_store_dwordx4 v[114:115], v[104:107], off
	s_nop 1
	v_lshl_add_u64 v[104:105], s[16:17], 0, v[112:113]
	global_store_dwordx4 v[104:105], v[108:111], off
	v_lshlrev_b64 v[104:105], 11, v[182:183]
	v_lshl_add_u64 v[104:105], v[104:105], 0, v[180:181]
	v_lshl_add_u64 v[108:109], v[104:105], 0, s[0:1]
	v_readlane_b32 s0, v252, 6
	v_readlane_b32 s1, v252, 7
	v_mul_f32_e32 v110, v68, v100
	v_fmamk_f32 v100, v110, 0xbc088889, v163
	v_lshl_add_u64 v[104:105], v[108:109], 1, s[0:1]
	global_load_dwordx4 v[104:107], v[104:105], off
	v_fma_f32 v100, -v110, v100, s5
	v_fma_f32 v100, -v110, v100, 0.5
	v_fma_f32 v100, -v110, v100, 1.0
	v_mul_f32_e32 v100, v110, v100
	v_cmp_le_f32_e32 vcc, s8, v110
	s_cbranch_vccnz .LBB0_428

; __device__ __forceinline__ unsigned cvt_pk_bf16(float lo, float hi) { unsigned r; asm volatile("v_cvt_pk_bf16_f32 %0, %1, %2" : "=v"(r) : "v"(lo), "v"(hi)); return r; }
; __device__ __forceinline__ float fsigmoid(float x) { return __builtin_amdgcn_rcpf(1.0f + __expf(-x)); }
;     __device__ __forceinline__ void operator()(const Acc& acc, const Unit& u, int wr, int wc, int fr, int fq) const {
;     ...
;                     for (int j = 0; j < 4; ++j) { const float r = fsigmoid(acc[ai][0][m][n][j] + ba[n][j]), ig = fsigmoid(acc[ai][1][m][n][j] + bi[n][j]);
;                         const float y = r * cc[n][j];
;                         float o1 = y * (1.0f - y * (0.5f - y * (0.16666667f - y * (0.041666668f - y * 0.008333334f))));
;                         if (__builtin_expect(__any(y >= 0.125f), 0)) { const float ome = 1.0f - __expf(-y); o1 = y < 0.125f ? o1 : ome; }
;                         om[n * 4 + j] = o1; uv[n * 4 + j] = sqrtf(o1 * (2.0f - o1)) * (ig * xv[n * 4 + j]); }
;                 u32x4 wa, wu; wa.x = cvt_pk_bf16(om[0], om[1]); wa.y = cvt_pk_bf16(om[2], om[3]); wa.z = cvt_pk_bf16(om[4], om[5]); wa.w = cvt_pk_bf16(om[6], om[7]);
;                 wu.x = cvt_pk_bf16(uv[0], uv[1]); wu.y = cvt_pk_bf16(uv[2], uv[3]); wu.z = cvt_pk_bf16(uv[4], uv[5]); wu.w = cvt_pk_bf16(uv[6], uv[7]);
;                 *(u32x4*)(Ao + off) = wa; *(u32x4*)(Uo + off) = wu; asm volatile("" ::: "memory"); }
.LBB0_368:
	v_sub_f32_e32 v110, 2.0, v98
	v_mul_f32_e32 v110, v98, v110
	v_mul_f32_e32 v111, 0x4f800000, v110
	v_cmp_gt_f32_e32 vcc, s10, v110
	v_add_f32_e32 v94, v94, v42
	v_mul_f32_e32 v94, 0xbfb8aa3b, v94
	v_cndmask_b32_e32 v110, v110, v111, vcc
	v_sqrt_f32_e32 v111, v110
	v_exp_f32_e32 v94, v94
	v_add_f32_e32 v95, v95, v43
	v_mul_f32_e32 v95, 0xbfb8aa3b, v95
	v_add_f32_e32 v94, 1.0, v94
	v_rcp_f32_e32 v94, v94
	v_exp_f32_e32 v95, v95
	s_waitcnt vmcnt(0)
	v_lshlrev_b32_e32 v112, 16, v107
	v_mul_f32_e32 v113, 0x37800000, v111
	v_cndmask_b32_e32 v111, v111, v113, vcc
	v_cmp_class_f32_e32 vcc, v110, v194
	v_mul_f32_e32 v94, v94, v112
	v_add_f32_e32 v93, v93, v41
	v_cndmask_b32_e32 v110, v111, v110, vcc
	v_mul_f32_e32 v110, v94, v110
	v_add_f32_e32 v94, 1.0, v95
	v_sub_f32_e32 v95, 2.0, v97
	v_mul_f32_e32 v95, v97, v95
	v_mul_f32_e32 v111, 0x4f800000, v95
	v_cmp_gt_f32_e32 vcc, s10, v95
	v_mul_f32_e32 v93, 0xbfb8aa3b, v93
	v_exp_f32_e32 v93, v93
	v_cndmask_b32_e32 v95, v95, v111, vcc
	v_sqrt_f32_e32 v111, v95
	v_and_b32_e32 v112, 0xffff0000, v106
	v_add_f32_e32 v93, 1.0, v93
	v_rcp_f32_e32 v93, v93
	s_nop 0
	v_mul_f32_e32 v93, v93, v112
	v_add_f32_e32 v92, v92, v40
	v_mul_f32_e32 v92, 0xbfb8aa3b, v92
	v_mul_f32_e32 v113, 0x37800000, v111
	v_cndmask_b32_e32 v111, v111, v113, vcc
	v_cmp_class_f32_e32 vcc, v95, v194
	v_exp_f32_e32 v92, v92
	v_lshlrev_b32_e32 v106, 16, v106
	v_cndmask_b32_e32 v95, v111, v95, vcc
	v_mul_f32_e32 v95, v93, v95
	v_sub_f32_e32 v93, 2.0, v96
	v_mul_f32_e32 v93, v96, v93
	v_mul_f32_e32 v111, 0x4f800000, v93
	v_cmp_gt_f32_e32 vcc, s10, v93
	v_add_f32_e32 v92, 1.0, v92
	v_rcp_f32_e32 v92, v92
	v_cndmask_b32_e32 v93, v93, v111, vcc
	v_sqrt_f32_e32 v111, v93
	v_add_f32_e32 v91, v91, v35
	v_mul_f32_e32 v92, v92, v106
	v_mul_f32_e32 v91, 0xbfb8aa3b, v91
	v_exp_f32_e32 v91, v91
	s_nop 0
	v_add_f32_e32 v91, 1.0, v91
	v_rcp_f32_e32 v91, v91
	v_mul_f32_e32 v112, 0x37800000, v111
	v_cndmask_b32_e32 v111, v111, v112, vcc
	v_cmp_class_f32_e32 vcc, v93, v194
	v_add_f32_e32 v90, v90, v34
	v_mul_f32_e32 v90, 0xbfb8aa3b, v90
	v_cndmask_b32_e32 v93, v111, v93, vcc
	v_mul_f32_e32 v106, v92, v93
	v_sub_f32_e32 v92, 2.0, v103
	v_mul_f32_e32 v92, v103, v92
	v_mul_f32_e32 v93, 0x4f800000, v92
	v_cmp_gt_f32_e32 vcc, s10, v92
	v_and_b32_e32 v111, 0xffff0000, v105
	v_mul_f32_e32 v91, v91, v111
	v_cndmask_b32_e32 v92, v92, v93, vcc
	v_sqrt_f32_e32 v93, v92
	v_exp_f32_e32 v90, v90
	v_lshlrev_b32_e32 v105, 16, v105
	v_add_f32_e32 v89, v89, v33
	v_add_f32_e32 v90, 1.0, v90
	v_rcp_f32_e32 v90, v90
	v_mul_f32_e32 v89, 0xbfb8aa3b, v89
	v_mul_f32_e32 v112, 0x37800000, v93
	v_cndmask_b32_e32 v93, v93, v112, vcc
	v_cmp_class_f32_e32 vcc, v92, v194
	v_mul_f32_e32 v90, v90, v105
	v_exp_f32_e32 v89, v89
	v_cndmask_b32_e32 v92, v93, v92, vcc
	v_mul_f32_e32 v93, v91, v92
	v_sub_f32_e32 v91, 2.0, v102
	v_mul_f32_e32 v91, v102, v91
	v_mul_f32_e32 v92, 0x4f800000, v91
	v_cmp_gt_f32_e32 vcc, s10, v91
	v_add_f32_e32 v89, 1.0, v89
	v_rcp_f32_e32 v89, v89
	v_cndmask_b32_e32 v91, v91, v92, vcc
	v_sqrt_f32_e32 v92, v91
	v_add_f32_e32 v88, v88, v32
	v_mul_f32_e32 v88, 0xbfb8aa3b, v88
	v_exp_f32_e32 v88, v88
	s_nop 0
	v_add_f32_e32 v88, 1.0, v88
	v_rcp_f32_e32 v88, v88
	v_rcp_f32_e32 v94, v94
	v_mul_f32_e32 v111, 0x37800000, v92
	v_cndmask_b32_e32 v92, v92, v111, vcc
	v_cmp_class_f32_e32 vcc, v91, v194
	v_add_f32_e32 v84, v84, v64
	v_mul_f32_e32 v84, 0xbfb8aa3b, v84
	v_cndmask_b32_e32 v91, v92, v91, vcc
	v_mul_f32_e32 v105, v90, v91
	v_sub_f32_e32 v90, 2.0, v101
	v_mul_f32_e32 v90, v101, v90
	v_mul_f32_e32 v91, 0x4f800000, v90
	v_cmp_gt_f32_e32 vcc, s10, v90
	v_and_b32_e32 v92, 0xffff0000, v104
	v_mul_f32_e32 v89, v89, v92
	v_cndmask_b32_e32 v90, v90, v91, vcc
	v_sqrt_f32_e32 v91, v90
	v_exp_f32_e32 v84, v84
	s_nop 0
	v_add_f32_e32 v84, 1.0, v84
	v_rcp_f32_e32 v84, v84
	s_nop 0
	v_mul_f32_e32 v111, 0x37800000, v91
	v_cndmask_b32_e32 v91, v91, v111, vcc
	v_cmp_class_f32_e32 vcc, v90, v194
	s_nop 1
	s_nop 0
	v_cndmask_b32_e32 v90, v91, v90, vcc
	v_mul_f32_e32 v92, v89, v90
	v_sub_f32_e32 v89, 2.0, v100
	v_mul_f32_e32 v89, v100, v89
	v_mul_f32_e32 v90, 0x4f800000, v89
	v_cmp_gt_f32_e32 vcc, s10, v89
	v_lshlrev_b32_e32 v91, 16, v104
	v_mul_f32_e32 v88, v88, v91
	v_cndmask_b32_e32 v89, v89, v90, vcc
	v_sqrt_f32_e32 v90, v89
	s_nop 0
	s_nop 0
	s_nop 1
	v_mul_f32_e32 v104, 0x37800000, v90
	v_cndmask_b32_e32 v90, v90, v104, vcc
	v_cmp_class_f32_e32 vcc, v89, v194
	s_nop 1
	s_nop 0
	v_cndmask_b32_e32 v89, v90, v89, vcc
	v_sub_f32_e32 v90, 2.0, v99
	v_mul_f32_e32 v90, v99, v90
	v_mul_f32_e32 v104, 0x4f800000, v90
	v_cmp_gt_f32_e32 vcc, s10, v90
	v_mul_f32_e32 v111, v88, v89
	v_and_b32_e32 v88, 0xffff0000, v107
	v_cndmask_b32_e32 v90, v90, v104, vcc
	v_sqrt_f32_e32 v104, v90
	v_mul_f32_e32 v88, v94, v88
	s_nop 0
	s_nop 1
	v_mul_f32_e32 v91, 0x37800000, v104
	v_cndmask_b32_e32 v89, v104, v91, vcc
	v_cmp_class_f32_e32 vcc, v90, v194
	s_mov_b64 s[0:1], 0x40000
	s_nop 0
	v_cndmask_b32_e32 v89, v89, v90, vcc
	v_mul_f32_e32 v104, v88, v89
	v_cvt_pk_bf16_f32 v88, v100, v101
	v_cvt_pk_bf16_f32 v89, v102, v103
	v_cvt_pk_bf16_f32 v90, v96, v97
	v_lshlrev_b64 v[96:97], 1, v[108:109]
	v_cvt_pk_bf16_f32 v91, v98, v99
	v_lshl_add_u64 v[98:99], s[12:13], 0, v[96:97]
	v_cvt_pk_bf16_f32 v92, v111, v92
	v_cvt_pk_bf16_f32 v93, v105, v93
	v_cvt_pk_bf16_f32 v94, v106, v95
	v_cvt_pk_bf16_f32 v95, v110, v104
	global_store_dwordx4 v[98:99], v[88:91], off
	s_nop 1
	v_lshl_add_u64 v[88:89], s[16:17], 0, v[96:97]
	global_store_dwordx4 v[88:89], v[92:95], off
	v_lshlrev_b64 v[88:89], 11, v[182:183]
	v_lshl_add_u64 v[88:89], v[88:89], 0, v[180:181]
	v_lshl_add_u64 v[92:93], v[88:89], 0, s[0:1]
	v_readlane_b32 s0, v252, 6
	v_readlane_b32 s1, v252, 7
	v_mul_f32_e32 v94, v68, v84
	v_fmamk_f32 v84, v94, 0xbc088889, v163
	v_lshl_add_u64 v[88:89], v[92:93], 1, s[0:1]
	global_load_dwordx4 v[88:91], v[88:89], off
	v_fma_f32 v84, -v94, v84, s5
	v_fma_f32 v84, -v94, v84, 0.5
	v_fma_f32 v84, -v94, v84, 1.0
	v_mul_f32_e32 v84, v94, v84
	v_cmp_le_f32_e32 vcc, s8, v94
	s_cbranch_vccnz .LBB0_436

; __device__ __forceinline__ unsigned cvt_pk_bf16(float lo, float hi) { unsigned r; asm volatile("v_cvt_pk_bf16_f32 %0, %1, %2" : "=v"(r) : "v"(lo), "v"(hi)); return r; }
; __device__ __forceinline__ float fsigmoid(float x) { return __builtin_amdgcn_rcpf(1.0f + __expf(-x)); }
;     __device__ __forceinline__ void operator()(const Acc& acc, const Unit& u, int wr, int wc, int fr, int fq) const {
;     ...
;                     for (int j = 0; j < 4; ++j) { const float r = fsigmoid(acc[ai][0][m][n][j] + ba[n][j]), ig = fsigmoid(acc[ai][1][m][n][j] + bi[n][j]);
;                         const float y = r * cc[n][j];
;                         float o1 = y * (1.0f - y * (0.5f - y * (0.16666667f - y * (0.041666668f - y * 0.008333334f))));
;                         if (__builtin_expect(__any(y >= 0.125f), 0)) { const float ome = 1.0f - __expf(-y); o1 = y < 0.125f ? o1 : ome; }
;                         om[n * 4 + j] = o1; uv[n * 4 + j] = sqrtf(o1 * (2.0f - o1)) * (ig * xv[n * 4 + j]); }
;                 u32x4 wa, wu; wa.x = cvt_pk_bf16(om[0], om[1]); wa.y = cvt_pk_bf16(om[2], om[3]); wa.z = cvt_pk_bf16(om[4], om[5]); wa.w = cvt_pk_bf16(om[6], om[7]);
;                 wu.x = cvt_pk_bf16(uv[0], uv[1]); wu.y = cvt_pk_bf16(uv[2], uv[3]); wu.z = cvt_pk_bf16(uv[4], uv[5]); wu.w = cvt_pk_bf16(uv[6], uv[7]);
;                 *(u32x4*)(Ao + off) = wa; *(u32x4*)(Uo + off) = wu; asm volatile("" ::: "memory"); }
.LBB0_376:
	v_sub_f32_e32 v94, 2.0, v82
	v_mul_f32_e32 v94, v82, v94
	v_mul_f32_e32 v95, 0x4f800000, v94
	v_cmp_gt_f32_e32 vcc, s10, v94
	v_add_f32_e32 v78, v78, v42
	v_mul_f32_e32 v78, 0xbfb8aa3b, v78
	v_cndmask_b32_e32 v94, v94, v95, vcc
	v_sqrt_f32_e32 v95, v94
	v_exp_f32_e32 v78, v78
	v_add_f32_e32 v79, v79, v43
	v_mul_f32_e32 v79, 0xbfb8aa3b, v79
	v_add_f32_e32 v78, 1.0, v78
	v_rcp_f32_e32 v78, v78
	v_exp_f32_e32 v79, v79
	s_waitcnt vmcnt(0)
	v_lshlrev_b32_e32 v96, 16, v91
	v_mul_f32_e32 v97, 0x37800000, v95
	v_cndmask_b32_e32 v95, v95, v97, vcc
	v_cmp_class_f32_e32 vcc, v94, v194
	v_mul_f32_e32 v78, v78, v96
	v_add_f32_e32 v77, v77, v41
	v_cndmask_b32_e32 v94, v95, v94, vcc
	v_mul_f32_e32 v94, v78, v94
	v_add_f32_e32 v78, 1.0, v79
	v_sub_f32_e32 v79, 2.0, v81
	v_mul_f32_e32 v79, v81, v79
	v_mul_f32_e32 v95, 0x4f800000, v79
	v_cmp_gt_f32_e32 vcc, s10, v79
	v_mul_f32_e32 v77, 0xbfb8aa3b, v77
	v_exp_f32_e32 v77, v77
	v_cndmask_b32_e32 v79, v79, v95, vcc
	v_sqrt_f32_e32 v95, v79
	v_and_b32_e32 v96, 0xffff0000, v90
	v_add_f32_e32 v77, 1.0, v77
	v_rcp_f32_e32 v77, v77
	s_nop 0
	v_mul_f32_e32 v77, v77, v96
	v_add_f32_e32 v76, v76, v40
	v_mul_f32_e32 v76, 0xbfb8aa3b, v76
	v_mul_f32_e32 v97, 0x37800000, v95
	v_cndmask_b32_e32 v95, v95, v97, vcc
	v_cmp_class_f32_e32 vcc, v79, v194
	v_exp_f32_e32 v76, v76
	v_lshlrev_b32_e32 v90, 16, v90
	v_cndmask_b32_e32 v79, v95, v79, vcc
	v_mul_f32_e32 v79, v77, v79
	v_sub_f32_e32 v77, 2.0, v80
	v_mul_f32_e32 v77, v80, v77
	v_mul_f32_e32 v95, 0x4f800000, v77
	v_cmp_gt_f32_e32 vcc, s10, v77
	v_add_f32_e32 v76, 1.0, v76
	v_rcp_f32_e32 v76, v76
	v_cndmask_b32_e32 v77, v77, v95, vcc
	v_sqrt_f32_e32 v95, v77
	v_add_f32_e32 v75, v75, v35
	v_mul_f32_e32 v76, v76, v90
	v_mul_f32_e32 v75, 0xbfb8aa3b, v75
	v_exp_f32_e32 v75, v75
	s_nop 0
	v_add_f32_e32 v75, 1.0, v75
	v_rcp_f32_e32 v75, v75
	v_mul_f32_e32 v96, 0x37800000, v95
	v_cndmask_b32_e32 v95, v95, v96, vcc
	v_cmp_class_f32_e32 vcc, v77, v194
	v_add_f32_e32 v74, v74, v34
	v_mul_f32_e32 v74, 0xbfb8aa3b, v74
	v_cndmask_b32_e32 v77, v95, v77, vcc
	v_mul_f32_e32 v90, v76, v77
	v_sub_f32_e32 v76, 2.0, v87
	v_mul_f32_e32 v76, v87, v76
	v_mul_f32_e32 v77, 0x4f800000, v76
	v_cmp_gt_f32_e32 vcc, s10, v76
	v_and_b32_e32 v95, 0xffff0000, v89
	v_mul_f32_e32 v75, v75, v95
	v_cndmask_b32_e32 v76, v76, v77, vcc
	v_sqrt_f32_e32 v77, v76
	v_exp_f32_e32 v74, v74
	v_lshlrev_b32_e32 v89, 16, v89
	v_add_f32_e32 v73, v73, v33
	v_add_f32_e32 v74, 1.0, v74
	v_rcp_f32_e32 v74, v74
	v_mul_f32_e32 v73, 0xbfb8aa3b, v73
	v_mul_f32_e32 v96, 0x37800000, v77
	v_cndmask_b32_e32 v77, v77, v96, vcc
	v_cmp_class_f32_e32 vcc, v76, v194
	v_mul_f32_e32 v74, v74, v89
	v_exp_f32_e32 v73, v73
	v_cndmask_b32_e32 v76, v77, v76, vcc
	v_mul_f32_e32 v77, v75, v76
	v_sub_f32_e32 v75, 2.0, v86
	v_mul_f32_e32 v75, v86, v75
	v_mul_f32_e32 v76, 0x4f800000, v75
	v_cmp_gt_f32_e32 vcc, s10, v75
	v_add_f32_e32 v73, 1.0, v73
	v_rcp_f32_e32 v73, v73
	v_cndmask_b32_e32 v75, v75, v76, vcc
	v_sqrt_f32_e32 v76, v75
	v_add_f32_e32 v72, v72, v32
	v_mul_f32_e32 v72, 0xbfb8aa3b, v72
	v_exp_f32_e32 v72, v72
	s_nop 0
	v_add_f32_e32 v72, 1.0, v72
	v_rcp_f32_e32 v72, v72
	v_rcp_f32_e32 v78, v78
	v_mul_f32_e32 v95, 0x37800000, v76
	v_cndmask_b32_e32 v76, v76, v95, vcc
	v_cmp_class_f32_e32 vcc, v75, v194
	v_add_f32_e32 v60, v60, v64
	v_mul_f32_e32 v60, 0xbfb8aa3b, v60
	v_cndmask_b32_e32 v75, v76, v75, vcc
	v_mul_f32_e32 v89, v74, v75
	v_sub_f32_e32 v74, 2.0, v85
	v_mul_f32_e32 v74, v85, v74
	v_mul_f32_e32 v75, 0x4f800000, v74
	v_cmp_gt_f32_e32 vcc, s10, v74
	v_and_b32_e32 v76, 0xffff0000, v88
	v_mul_f32_e32 v73, v73, v76
	v_cndmask_b32_e32 v74, v74, v75, vcc
	v_sqrt_f32_e32 v75, v74
	v_exp_f32_e32 v60, v60
	s_nop 0
	v_add_f32_e32 v60, 1.0, v60
	v_rcp_f32_e32 v60, v60
	s_nop 0
	v_mul_f32_e32 v95, 0x37800000, v75
	v_cndmask_b32_e32 v75, v75, v95, vcc
	v_cmp_class_f32_e32 vcc, v74, v194
	s_nop 1
	s_nop 0
	v_cndmask_b32_e32 v74, v75, v74, vcc
	v_mul_f32_e32 v76, v73, v74
	v_sub_f32_e32 v73, 2.0, v84
	v_mul_f32_e32 v73, v84, v73
	v_mul_f32_e32 v74, 0x4f800000, v73
	v_cmp_gt_f32_e32 vcc, s10, v73
	v_lshlrev_b32_e32 v75, 16, v88
	v_mul_f32_e32 v72, v72, v75
	v_cndmask_b32_e32 v73, v73, v74, vcc
	v_sqrt_f32_e32 v74, v73
	s_nop 0
	s_nop 0
	s_nop 1
	v_mul_f32_e32 v88, 0x37800000, v74
	v_cndmask_b32_e32 v74, v74, v88, vcc
	v_cmp_class_f32_e32 vcc, v73, v194
	s_nop 1
	s_nop 0
	v_cndmask_b32_e32 v73, v74, v73, vcc
	v_sub_f32_e32 v74, 2.0, v83
	v_mul_f32_e32 v74, v83, v74
	v_mul_f32_e32 v88, 0x4f800000, v74
	v_cmp_gt_f32_e32 vcc, s10, v74
	v_mul_f32_e32 v95, v72, v73
	v_and_b32_e32 v72, 0xffff0000, v91
	v_cndmask_b32_e32 v74, v74, v88, vcc
	v_sqrt_f32_e32 v88, v74
	v_mul_f32_e32 v72, v78, v72
	s_nop 0
	s_nop 1
	v_mul_f32_e32 v75, 0x37800000, v88
	v_cndmask_b32_e32 v73, v88, v75, vcc
	v_cmp_class_f32_e32 vcc, v74, v194
	s_mov_b64 s[0:1], 0x48000
	s_nop 0
	v_cndmask_b32_e32 v73, v73, v74, vcc
	v_mul_f32_e32 v88, v72, v73
	v_cvt_pk_bf16_f32 v72, v84, v85
	v_cvt_pk_bf16_f32 v73, v86, v87
	v_cvt_pk_bf16_f32 v74, v80, v81
	v_lshlrev_b64 v[80:81], 1, v[92:93]
	v_cvt_pk_bf16_f32 v75, v82, v83
	v_lshl_add_u64 v[82:83], s[12:13], 0, v[80:81]
	v_cvt_pk_bf16_f32 v76, v95, v76
	v_cvt_pk_bf16_f32 v77, v89, v77
	v_cvt_pk_bf16_f32 v78, v90, v79
	v_cvt_pk_bf16_f32 v79, v94, v88
	global_store_dwordx4 v[82:83], v[72:75], off
	s_nop 1
	v_lshl_add_u64 v[72:73], s[16:17], 0, v[80:81]
	global_store_dwordx4 v[72:73], v[76:79], off
	v_lshlrev_b64 v[72:73], 11, v[182:183]
	v_lshl_add_u64 v[72:73], v[72:73], 0, v[180:181]
	v_lshl_add_u64 v[76:77], v[72:73], 0, s[0:1]
	v_readlane_b32 s0, v252, 6
	v_readlane_b32 s1, v252, 7
	v_mul_f32_e32 v78, v68, v60
	v_fmamk_f32 v60, v78, 0xbc088889, v163
	v_lshl_add_u64 v[72:73], v[76:77], 1, s[0:1]
	global_load_dwordx4 v[72:75], v[72:73], off
	v_fma_f32 v60, -v78, v60, s5
	v_fma_f32 v60, -v78, v60, 0.5
	v_fma_f32 v60, -v78, v60, 1.0
	v_mul_f32_e32 v60, v78, v60
	v_cmp_le_f32_e32 vcc, s8, v78
	s_cbranch_vccnz .LBB0_444

; __device__ __forceinline__ unsigned cvt_pk_bf16(float lo, float hi) { unsigned r; asm volatile("v_cvt_pk_bf16_f32 %0, %1, %2" : "=v"(r) : "v"(lo), "v"(hi)); return r; }
; __device__ __forceinline__ float fsigmoid(float x) { return __builtin_amdgcn_rcpf(1.0f + __expf(-x)); }
;     __device__ __forceinline__ void operator()(const Acc& acc, const Unit& u, int wr, int wc, int fr, int fq) const {
;     ...
;                     for (int j = 0; j < 4; ++j) { const float r = fsigmoid(acc[ai][0][m][n][j] + ba[n][j]), ig = fsigmoid(acc[ai][1][m][n][j] + bi[n][j]);
;                         const float y = r * cc[n][j];
;                         float o1 = y * (1.0f - y * (0.5f - y * (0.16666667f - y * (0.041666668f - y * 0.008333334f))));
;                         if (__builtin_expect(__any(y >= 0.125f), 0)) { const float ome = 1.0f - __expf(-y); o1 = y < 0.125f ? o1 : ome; }
;                         om[n * 4 + j] = o1; uv[n * 4 + j] = sqrtf(o1 * (2.0f - o1)) * (ig * xv[n * 4 + j]); }
;                 u32x4 wa, wu; wa.x = cvt_pk_bf16(om[0], om[1]); wa.y = cvt_pk_bf16(om[2], om[3]); wa.z = cvt_pk_bf16(om[4], om[5]); wa.w = cvt_pk_bf16(om[6], om[7]);
;                 wu.x = cvt_pk_bf16(uv[0], uv[1]); wu.y = cvt_pk_bf16(uv[2], uv[3]); wu.z = cvt_pk_bf16(uv[4], uv[5]); wu.w = cvt_pk_bf16(uv[6], uv[7]);
;                 *(u32x4*)(Ao + off) = wa; *(u32x4*)(Uo + off) = wu; asm volatile("" ::: "memory"); }
.LBB0_384:
	v_sub_f32_e32 v78, 2.0, v54
	v_mul_f32_e32 v78, v54, v78
	v_mul_f32_e32 v79, 0x4f800000, v78
	v_cmp_gt_f32_e32 vcc, s10, v78
	v_add_f32_e32 v46, v46, v42
	v_mul_f32_e32 v46, 0xbfb8aa3b, v46
	v_cndmask_b32_e32 v78, v78, v79, vcc
	v_sqrt_f32_e32 v79, v78
	v_exp_f32_e32 v46, v46
	v_add_f32_e32 v47, v47, v43
	v_mul_f32_e32 v47, 0xbfb8aa3b, v47
	v_add_f32_e32 v46, 1.0, v46
	v_rcp_f32_e32 v46, v46
	v_exp_f32_e32 v47, v47
	s_waitcnt vmcnt(0)
	v_lshlrev_b32_e32 v80, 16, v75
	v_mul_f32_e32 v81, 0x37800000, v79
	v_cndmask_b32_e32 v79, v79, v81, vcc
	v_cmp_class_f32_e32 vcc, v78, v194
	v_mul_f32_e32 v46, v46, v80
	v_add_f32_e32 v45, v45, v41
	v_cndmask_b32_e32 v78, v79, v78, vcc
	v_mul_f32_e32 v78, v46, v78
	v_add_f32_e32 v46, 1.0, v47
	v_sub_f32_e32 v47, 2.0, v53
	v_mul_f32_e32 v47, v53, v47
	v_mul_f32_e32 v79, 0x4f800000, v47
	v_cmp_gt_f32_e32 vcc, s10, v47
	v_mul_f32_e32 v45, 0xbfb8aa3b, v45
	v_exp_f32_e32 v45, v45
	v_cndmask_b32_e32 v47, v47, v79, vcc
	v_sqrt_f32_e32 v79, v47
	v_and_b32_e32 v80, 0xffff0000, v74
	v_add_f32_e32 v45, 1.0, v45
	v_rcp_f32_e32 v45, v45
	s_nop 0
	v_mul_f32_e32 v45, v45, v80
	v_add_f32_e32 v44, v44, v40
	v_mul_f32_e32 v44, 0xbfb8aa3b, v44
	v_mul_f32_e32 v81, 0x37800000, v79
	v_cndmask_b32_e32 v79, v79, v81, vcc
	v_cmp_class_f32_e32 vcc, v47, v194
	v_exp_f32_e32 v44, v44
	v_lshlrev_b32_e32 v74, 16, v74
	v_cndmask_b32_e32 v47, v79, v47, vcc
	v_mul_f32_e32 v47, v45, v47
	v_sub_f32_e32 v45, 2.0, v52
	v_mul_f32_e32 v45, v52, v45
	v_mul_f32_e32 v79, 0x4f800000, v45
	v_cmp_gt_f32_e32 vcc, s10, v45
	v_add_f32_e32 v44, 1.0, v44
	v_rcp_f32_e32 v44, v44
	v_cndmask_b32_e32 v45, v45, v79, vcc
	v_sqrt_f32_e32 v79, v45
	v_add_f32_e32 v39, v39, v35
	v_mul_f32_e32 v44, v44, v74
	v_mul_f32_e32 v39, 0xbfb8aa3b, v39
	v_exp_f32_e32 v39, v39
	s_nop 0
	v_add_f32_e32 v39, 1.0, v39
	v_rcp_f32_e32 v39, v39
	v_mul_f32_e32 v80, 0x37800000, v79
	v_cndmask_b32_e32 v79, v79, v80, vcc
	v_cmp_class_f32_e32 vcc, v45, v194
	v_add_f32_e32 v38, v38, v34
	v_mul_f32_e32 v38, 0xbfb8aa3b, v38
	v_cndmask_b32_e32 v45, v79, v45, vcc
	v_mul_f32_e32 v74, v44, v45
	v_sub_f32_e32 v44, 2.0, v63
	v_mul_f32_e32 v44, v63, v44
	v_mul_f32_e32 v45, 0x4f800000, v44
	v_cmp_gt_f32_e32 vcc, s10, v44
	v_and_b32_e32 v79, 0xffff0000, v73
	v_mul_f32_e32 v39, v39, v79
	v_cndmask_b32_e32 v44, v44, v45, vcc
	v_sqrt_f32_e32 v45, v44
	v_exp_f32_e32 v38, v38
	v_lshlrev_b32_e32 v73, 16, v73
	v_add_f32_e32 v37, v37, v33
	v_add_f32_e32 v38, 1.0, v38
	v_rcp_f32_e32 v38, v38
	v_mul_f32_e32 v37, 0xbfb8aa3b, v37
	v_mul_f32_e32 v80, 0x37800000, v45
	v_cndmask_b32_e32 v45, v45, v80, vcc
	v_cmp_class_f32_e32 vcc, v44, v194
	v_mul_f32_e32 v38, v38, v73
	v_exp_f32_e32 v37, v37
	v_cndmask_b32_e32 v44, v45, v44, vcc
	v_mul_f32_e32 v45, v39, v44
	v_sub_f32_e32 v39, 2.0, v62
	v_mul_f32_e32 v39, v62, v39
	v_mul_f32_e32 v44, 0x4f800000, v39
	v_cmp_gt_f32_e32 vcc, s10, v39
	v_add_f32_e32 v37, 1.0, v37
	v_rcp_f32_e32 v37, v37
	v_cndmask_b32_e32 v39, v39, v44, vcc
	v_sqrt_f32_e32 v44, v39
	v_add_f32_e32 v36, v36, v32
	v_mul_f32_e32 v36, 0xbfb8aa3b, v36
	v_exp_f32_e32 v36, v36
	s_nop 0
	v_add_f32_e32 v36, 1.0, v36
	v_rcp_f32_e32 v36, v36
	v_rcp_f32_e32 v46, v46
	v_mul_f32_e32 v79, 0x37800000, v44
	v_cndmask_b32_e32 v44, v44, v79, vcc
	v_cmp_class_f32_e32 vcc, v39, v194
	v_add_f32_e32 v28, v28, v64
	v_mul_f32_e32 v28, 0xbfb8aa3b, v28
	v_cndmask_b32_e32 v39, v44, v39, vcc
	v_mul_f32_e32 v73, v38, v39
	v_sub_f32_e32 v38, 2.0, v61
	v_mul_f32_e32 v38, v61, v38
	v_mul_f32_e32 v39, 0x4f800000, v38
	v_cmp_gt_f32_e32 vcc, s10, v38
	v_and_b32_e32 v44, 0xffff0000, v72
	v_mul_f32_e32 v37, v37, v44
	v_cndmask_b32_e32 v38, v38, v39, vcc
	v_sqrt_f32_e32 v39, v38
	v_exp_f32_e32 v28, v28
	s_nop 0
	v_add_f32_e32 v28, 1.0, v28
	v_rcp_f32_e32 v28, v28
	s_nop 0
	v_mul_f32_e32 v79, 0x37800000, v39
	v_cndmask_b32_e32 v39, v39, v79, vcc
	v_cmp_class_f32_e32 vcc, v38, v194
	s_nop 1
	s_nop 0
	v_cndmask_b32_e32 v38, v39, v38, vcc
	v_mul_f32_e32 v44, v37, v38
	v_sub_f32_e32 v37, 2.0, v60
	v_mul_f32_e32 v37, v60, v37
	v_mul_f32_e32 v38, 0x4f800000, v37
	v_cmp_gt_f32_e32 vcc, s10, v37
	v_lshlrev_b32_e32 v39, 16, v72
	v_mul_f32_e32 v36, v36, v39
	v_cndmask_b32_e32 v37, v37, v38, vcc
	v_sqrt_f32_e32 v38, v37
	s_nop 0
	s_nop 0
	s_nop 1
	v_mul_f32_e32 v72, 0x37800000, v38
	v_cndmask_b32_e32 v38, v38, v72, vcc
	v_cmp_class_f32_e32 vcc, v37, v194
	s_nop 1
	s_nop 0
	v_cndmask_b32_e32 v37, v38, v37, vcc
	v_sub_f32_e32 v38, 2.0, v55
	v_mul_f32_e32 v38, v55, v38
	v_mul_f32_e32 v72, 0x4f800000, v38
	v_cmp_gt_f32_e32 vcc, s10, v38
	v_mul_f32_e32 v79, v36, v37
	v_and_b32_e32 v36, 0xffff0000, v75
	v_cndmask_b32_e32 v38, v38, v72, vcc
	v_sqrt_f32_e32 v72, v38
	v_mul_f32_e32 v36, v46, v36
	s_nop 0
	s_nop 1
	v_mul_f32_e32 v39, 0x37800000, v72
	v_cndmask_b32_e32 v37, v72, v39, vcc
	v_cmp_class_f32_e32 vcc, v38, v194
	s_mov_b64 s[0:1], 0x50000
	s_nop 0
	v_cndmask_b32_e32 v37, v37, v38, vcc
	v_mul_f32_e32 v72, v36, v37
	v_cvt_pk_bf16_f32 v36, v60, v61
	v_cvt_pk_bf16_f32 v37, v62, v63
	v_cvt_pk_bf16_f32 v38, v52, v53
	v_lshlrev_b64 v[52:53], 1, v[76:77]
	v_cvt_pk_bf16_f32 v39, v54, v55
	v_lshl_add_u64 v[54:55], s[12:13], 0, v[52:53]
	v_cvt_pk_bf16_f32 v44, v79, v44
	v_cvt_pk_bf16_f32 v45, v73, v45
	v_cvt_pk_bf16_f32 v46, v74, v47
	v_cvt_pk_bf16_f32 v47, v78, v72
	global_store_dwordx4 v[54:55], v[36:39], off
	s_nop 1
	v_lshl_add_u64 v[36:37], s[16:17], 0, v[52:53]
	global_store_dwordx4 v[36:37], v[44:47], off
	v_lshlrev_b64 v[36:37], 11, v[182:183]
	v_lshl_add_u64 v[36:37], v[36:37], 0, v[180:181]
	v_lshl_add_u64 v[44:45], v[36:37], 0, s[0:1]
	v_readlane_b32 s0, v252, 6
	v_readlane_b32 s1, v252, 7
	v_mul_f32_e32 v46, v68, v28
	v_fmamk_f32 v28, v46, 0xbc088889, v163
	v_lshl_add_u64 v[36:37], v[44:45], 1, s[0:1]
	global_load_dwordx4 v[36:39], v[36:37], off
	v_fma_f32 v28, -v46, v28, s5
	v_fma_f32 v28, -v46, v28, 0.5
	v_fma_f32 v28, -v46, v28, 1.0
	v_mul_f32_e32 v28, v46, v28
	v_cmp_le_f32_e32 vcc, s8, v46
	s_cbranch_vccnz .LBB0_452

; __device__ __forceinline__ unsigned cvt_pk_bf16(float lo, float hi) { unsigned r; asm volatile("v_cvt_pk_bf16_f32 %0, %1, %2" : "=v"(r) : "v"(lo), "v"(hi)); return r; }
; __device__ __forceinline__ float fsigmoid(float x) { return __builtin_amdgcn_rcpf(1.0f + __expf(-x)); }
;     __device__ __forceinline__ void operator()(const Acc& acc, const Unit& u, int wr, int wc, int fr, int fq) const {
;     ...
;                     for (int j = 0; j < 4; ++j) { const float r = fsigmoid(acc[ai][0][m][n][j] + ba[n][j]), ig = fsigmoid(acc[ai][1][m][n][j] + bi[n][j]);
;                         const float y = r * cc[n][j];
;                         float o1 = y * (1.0f - y * (0.5f - y * (0.16666667f - y * (0.041666668f - y * 0.008333334f))));
;                         if (__builtin_expect(__any(y >= 0.125f), 0)) { const float ome = 1.0f - __expf(-y); o1 = y < 0.125f ? o1 : ome; }
;                         om[n * 4 + j] = o1; uv[n * 4 + j] = sqrtf(o1 * (2.0f - o1)) * (ig * xv[n * 4 + j]); }
;                 u32x4 wa, wu; wa.x = cvt_pk_bf16(om[0], om[1]); wa.y = cvt_pk_bf16(om[2], om[3]); wa.z = cvt_pk_bf16(om[4], om[5]); wa.w = cvt_pk_bf16(om[6], om[7]);
;                 wu.x = cvt_pk_bf16(uv[0], uv[1]); wu.y = cvt_pk_bf16(uv[2], uv[3]); wu.z = cvt_pk_bf16(uv[4], uv[5]); wu.w = cvt_pk_bf16(uv[6], uv[7]);
;                 *(u32x4*)(Ao + off) = wa; *(u32x4*)(Uo + off) = wu; asm volatile("" ::: "memory"); }
.LBB0_392:
	v_sub_f32_e32 v46, 2.0, v26
	v_mul_f32_e32 v46, v26, v46
	v_mul_f32_e32 v47, 0x4f800000, v46
	v_cmp_gt_f32_e32 vcc, s10, v46
	v_add_f32_e32 v22, v22, v42
	v_mul_f32_e32 v22, 0xbfb8aa3b, v22
	v_cndmask_b32_e32 v46, v46, v47, vcc
	v_sqrt_f32_e32 v47, v46
	v_exp_f32_e32 v22, v22
	v_add_f32_e32 v23, v23, v43
	v_mul_f32_e32 v23, 0xbfb8aa3b, v23
	v_add_f32_e32 v22, 1.0, v22
	v_rcp_f32_e32 v22, v22
	v_exp_f32_e32 v23, v23
	s_waitcnt vmcnt(0)
	v_lshlrev_b32_e32 v52, 16, v39
	v_mul_f32_e32 v53, 0x37800000, v47
	v_cndmask_b32_e32 v47, v47, v53, vcc
	v_cmp_class_f32_e32 vcc, v46, v194
	v_mul_f32_e32 v22, v22, v52
	v_add_f32_e32 v21, v21, v41
	v_cndmask_b32_e32 v46, v47, v46, vcc
	v_mul_f32_e32 v46, v22, v46
	v_add_f32_e32 v22, 1.0, v23
	v_sub_f32_e32 v23, 2.0, v25
	v_mul_f32_e32 v23, v25, v23
	v_mul_f32_e32 v47, 0x4f800000, v23
	v_cmp_gt_f32_e32 vcc, s10, v23
	v_mul_f32_e32 v21, 0xbfb8aa3b, v21
	v_exp_f32_e32 v21, v21
	v_cndmask_b32_e32 v23, v23, v47, vcc
	v_sqrt_f32_e32 v47, v23
	v_and_b32_e32 v52, 0xffff0000, v38
	v_add_f32_e32 v21, 1.0, v21
	v_rcp_f32_e32 v21, v21
	s_nop 0
	v_mul_f32_e32 v21, v21, v52
	v_add_f32_e32 v20, v20, v40
	v_mul_f32_e32 v20, 0xbfb8aa3b, v20
	v_mul_f32_e32 v53, 0x37800000, v47
	v_cndmask_b32_e32 v47, v47, v53, vcc
	v_cmp_class_f32_e32 vcc, v23, v194
	v_exp_f32_e32 v20, v20
	v_lshlrev_b32_e32 v38, 16, v38
	v_cndmask_b32_e32 v23, v47, v23, vcc
	v_mul_f32_e32 v23, v21, v23
	v_sub_f32_e32 v21, 2.0, v24
	v_mul_f32_e32 v21, v24, v21
	v_mul_f32_e32 v47, 0x4f800000, v21
	v_cmp_gt_f32_e32 vcc, s10, v21
	v_add_f32_e32 v20, 1.0, v20
	v_rcp_f32_e32 v20, v20
	v_cndmask_b32_e32 v21, v21, v47, vcc
	v_sqrt_f32_e32 v47, v21
	v_add_f32_e32 v19, v19, v35
	v_mul_f32_e32 v20, v20, v38
	v_mul_f32_e32 v19, 0xbfb8aa3b, v19
	v_exp_f32_e32 v19, v19
	s_nop 0
	v_add_f32_e32 v19, 1.0, v19
	v_rcp_f32_e32 v19, v19
	v_mul_f32_e32 v52, 0x37800000, v47
	v_cndmask_b32_e32 v47, v47, v52, vcc
	v_cmp_class_f32_e32 vcc, v21, v194
	v_add_f32_e32 v18, v18, v34
	v_mul_f32_e32 v18, 0xbfb8aa3b, v18
	v_cndmask_b32_e32 v21, v47, v21, vcc
	v_mul_f32_e32 v38, v20, v21
	v_sub_f32_e32 v20, 2.0, v31
	v_mul_f32_e32 v20, v31, v20
	v_mul_f32_e32 v21, 0x4f800000, v20
	v_cmp_gt_f32_e32 vcc, s10, v20
	v_and_b32_e32 v47, 0xffff0000, v37
	v_mul_f32_e32 v19, v19, v47
	v_cndmask_b32_e32 v20, v20, v21, vcc
	v_sqrt_f32_e32 v21, v20
	v_exp_f32_e32 v18, v18
	v_lshlrev_b32_e32 v37, 16, v37
	v_add_f32_e32 v17, v17, v33
	v_add_f32_e32 v18, 1.0, v18
	v_rcp_f32_e32 v18, v18
	v_mul_f32_e32 v17, 0xbfb8aa3b, v17
	v_mul_f32_e32 v52, 0x37800000, v21
	v_cndmask_b32_e32 v21, v21, v52, vcc
	v_cmp_class_f32_e32 vcc, v20, v194
	v_mul_f32_e32 v18, v18, v37
	v_exp_f32_e32 v17, v17
	v_cndmask_b32_e32 v20, v21, v20, vcc
	v_mul_f32_e32 v21, v19, v20
	v_sub_f32_e32 v19, 2.0, v30
	v_mul_f32_e32 v19, v30, v19
	v_mul_f32_e32 v20, 0x4f800000, v19
	v_cmp_gt_f32_e32 vcc, s10, v19
	v_add_f32_e32 v17, 1.0, v17
	v_rcp_f32_e32 v17, v17
	v_cndmask_b32_e32 v19, v19, v20, vcc
	v_sqrt_f32_e32 v20, v19
	v_add_f32_e32 v16, v16, v32
	v_mul_f32_e32 v16, 0xbfb8aa3b, v16
	v_exp_f32_e32 v16, v16
	s_nop 0
	v_add_f32_e32 v16, 1.0, v16
	v_rcp_f32_e32 v16, v16
	v_rcp_f32_e32 v22, v22
	v_mul_f32_e32 v47, 0x37800000, v20
	v_cndmask_b32_e32 v20, v20, v47, vcc
	v_cmp_class_f32_e32 vcc, v19, v194
	v_add_f32_e32 v12, v12, v64
	v_mul_f32_e32 v12, 0xbfb8aa3b, v12
	v_cndmask_b32_e32 v19, v20, v19, vcc
	v_mul_f32_e32 v37, v18, v19
	v_sub_f32_e32 v18, 2.0, v29
	v_mul_f32_e32 v18, v29, v18
	v_mul_f32_e32 v19, 0x4f800000, v18
	v_cmp_gt_f32_e32 vcc, s10, v18
	v_and_b32_e32 v20, 0xffff0000, v36
	v_mul_f32_e32 v17, v17, v20
	v_cndmask_b32_e32 v18, v18, v19, vcc
	v_sqrt_f32_e32 v19, v18
	v_exp_f32_e32 v12, v12
	s_nop 0
	v_add_f32_e32 v12, 1.0, v12
	v_rcp_f32_e32 v12, v12
	s_nop 0
	v_mul_f32_e32 v47, 0x37800000, v19
	v_cndmask_b32_e32 v19, v19, v47, vcc
	v_cmp_class_f32_e32 vcc, v18, v194
	s_nop 1
	s_nop 0
	v_cndmask_b32_e32 v18, v19, v18, vcc
	v_mul_f32_e32 v20, v17, v18
	v_sub_f32_e32 v17, 2.0, v28
	v_mul_f32_e32 v17, v28, v17
	v_mul_f32_e32 v18, 0x4f800000, v17
	v_cmp_gt_f32_e32 vcc, s10, v17
	v_lshlrev_b32_e32 v19, 16, v36
	v_mul_f32_e32 v16, v16, v19
	v_cndmask_b32_e32 v17, v17, v18, vcc
	v_sqrt_f32_e32 v18, v17
	s_nop 0
	s_nop 0
	s_nop 1
	v_mul_f32_e32 v36, 0x37800000, v18
	v_cndmask_b32_e32 v18, v18, v36, vcc
	v_cmp_class_f32_e32 vcc, v17, v194
	s_nop 1
	s_nop 0
	v_cndmask_b32_e32 v17, v18, v17, vcc
	v_sub_f32_e32 v18, 2.0, v27
	v_mul_f32_e32 v18, v27, v18
	v_mul_f32_e32 v36, 0x4f800000, v18
	v_cmp_gt_f32_e32 vcc, s10, v18
	v_mul_f32_e32 v47, v16, v17
	v_and_b32_e32 v16, 0xffff0000, v39
	v_cndmask_b32_e32 v18, v18, v36, vcc
	v_sqrt_f32_e32 v36, v18
	v_mul_f32_e32 v16, v22, v16
	s_nop 0
	s_nop 1
	v_mul_f32_e32 v19, 0x37800000, v36
	v_cndmask_b32_e32 v17, v36, v19, vcc
	v_cmp_class_f32_e32 vcc, v18, v194
	s_mov_b64 s[0:1], 0x58000
	s_nop 0
	v_cndmask_b32_e32 v17, v17, v18, vcc
	v_mul_f32_e32 v36, v16, v17
	v_cvt_pk_bf16_f32 v16, v28, v29
	v_cvt_pk_bf16_f32 v17, v30, v31
	v_cvt_pk_bf16_f32 v18, v24, v25
	v_lshlrev_b64 v[24:25], 1, v[44:45]
	v_cvt_pk_bf16_f32 v19, v26, v27
	v_lshl_add_u64 v[26:27], s[12:13], 0, v[24:25]
	v_cvt_pk_bf16_f32 v20, v47, v20
	v_cvt_pk_bf16_f32 v21, v37, v21
	v_cvt_pk_bf16_f32 v22, v38, v23
	v_cvt_pk_bf16_f32 v23, v46, v36
	global_store_dwordx4 v[26:27], v[16:19], off
	s_nop 1
	v_lshl_add_u64 v[16:17], s[16:17], 0, v[24:25]
	global_store_dwordx4 v[16:17], v[20:23], off
	v_lshlrev_b64 v[16:17], 11, v[182:183]
	v_lshl_add_u64 v[16:17], v[16:17], 0, v[180:181]
	v_lshl_add_u64 v[20:21], v[16:17], 0, s[0:1]
	v_readlane_b32 s0, v252, 6
	v_readlane_b32 s1, v252, 7
	v_mul_f32_e32 v22, v68, v12
	v_fmamk_f32 v12, v22, 0xbc088889, v163
	v_lshl_add_u64 v[16:17], v[20:21], 1, s[0:1]
	global_load_dwordx4 v[16:19], v[16:17], off
	v_fma_f32 v12, -v22, v12, s5
	v_fma_f32 v12, -v22, v12, 0.5
	v_fma_f32 v12, -v22, v12, 1.0
	v_mul_f32_e32 v12, v22, v12
	v_cmp_le_f32_e32 vcc, s8, v22
	s_cbranch_vccnz .LBB0_460
